# attention map-0 result parking: lane-contiguous scratch layout (each park / reload instruction moves 1 KiB of whole lines instead of 64 scattered 16-byte pieces)
# speedup vs baseline: 1.0081x; 1.0081x over previous
.LBB0_502:
	s_xor_b64 s[2:3], s[10:11], -1
	s_and_b64 s[10:11], s[10:11], exec
	v_mbcnt_lo_u32_b32 v0, -1, 0
	v_mbcnt_hi_u32_b32 v0, -1, v0
	s_cselect_b32 s21, s55, s53
	v_add_u32_e32 v5, s97, v0
	v_and_b32_e32 v8, 31, v0
	v_bfe_u32 v9, v0, 5, 1
	v_lshrrev_b32_e32 v3, 1, v0
	v_readfirstlane_b32 s10, v5
	v_bfe_u32 v4, v0, 1, 3
	v_lshlrev_b32_e32 v6, 7, v8
	v_bitop3_b32 v3, v9, v3, 7 bitop3:0x78
	s_ashr_i32 s22, s10, 6
	v_lshl_or_b32 v205, v3, 4, v6
	v_bitop3_b32 v3, v9, v4, 2 bitop3:0x36
	s_lshl_b32 s10, s21, 8
	s_lshl_b32 s11, s22, 5
	v_lshl_or_b32 v206, v3, 4, v6
	v_bitop3_b32 v3, v9, v4, 4 bitop3:0x36
	s_add_i32 s20, s11, s10
	v_lshl_or_b32 v207, v3, 4, v6
	v_bitop3_b32 v3, v9, v4, 6 bitop3:0x36
	v_or_b32_e32 v4, s11, v8
	s_lshl_b32 s11, s22, 2
	v_lshl_or_b32 v208, v3, 4, v6
	v_and_b32_e32 v3, 7, v0
	v_mul_lo_u32 v6, v4, s87
	v_lshlrev_b32_e32 v4, 4, v9
	v_readlane_b32 s12, v251, 34
	v_bfe_u32 v7, v0, 4, 2
	s_and_b32 s11, s11, 4
	v_add3_u32 v209, s12, v6, v4
	v_lshlrev_b32_e32 v6, 3, v0
	v_bitop3_b32 v10, s11, v3, v7 bitop3:0x36
	s_lshl_b32 s10, s22, 9
	v_and_b32_e32 v6, 0x1c0, v6
	v_lshlrev_b32_e32 v10, 3, v10
	v_or3_b32 v210, v10, s10, v6
	v_add_u32_e32 v10, 0xffffffa0, v5
	v_cvt_f32_u32_e32 v11, v10
	s_lshl_b32 s13, s22, 10
	v_or_b32_e32 v6, s13, v6
	v_bitop3_b32 v0, v7, v0, 7 bitop3:0x78
	v_lshl_or_b32 v211, v0, 3, v6
	v_mul_f32_e32 v0, 0x3d800000, v11
	s_mov_b32 s10, 0x800000
	v_cmp_gt_f32_e32 vcc, s10, v0
	v_bitop3_b32 v7, v7, v3, 4 bitop3:0x36
	v_lshlrev_b32_e32 v7, 3, v7
	v_cndmask_b32_e64 v11, 0, 32, vcc
	v_ldexp_f32 v0, v0, v11
	v_log_f32_e32 v0, v0
	s_movk_i32 s10, 0x200
	v_or3_b32 v212, v7, v6, s10
	s_mov_b32 s10, 0x3f317217
	v_mul_f32_e32 v6, 0x3f317217, v0
	v_fma_f32 v6, v0, s10, -v6
	v_fmac_f32_e32 v6, 0x3377d1cf, v0
	s_mov_b32 s10, 0x7f800000
	v_fmac_f32_e32 v6, 0x3f317217, v0
	v_cmp_lt_f32_e64 s[40:41], |v0|, s10
	s_mov_b32 s14, 0x40051592
	s_lshl_b32 s59, s21, 2
	v_cndmask_b32_e64 v0, v0, v6, s[40:41]
	v_mov_b32_e32 v6, 0x41b17218
	v_cndmask_b32_e32 v6, 0, v6, vcc
	v_sub_f32_e32 v0, v0, v6
	v_div_scale_f32 v6, s[10:11], s14, s14, v0
	v_rcp_f32_e32 v7, v6
	s_lshl_b32 s10, s22, 11
	s_add_i32 s61, s10, 0
	s_movk_i32 s10, 0x140
	v_fma_f32 v11, -v6, v7, 1.0
	v_fmac_f32_e32 v7, v11, v7
	v_div_scale_f32 v11, vcc, v0, s14, v0
	v_mul_f32_e32 v12, v11, v7
	v_fma_f32 v13, -v6, v12, v11
	v_fmac_f32_e32 v12, v13, v7
	v_fma_f32 v6, -v6, v12, v11
	v_div_fmas_f32 v6, v6, v7, v12
	v_div_fixup_f32 v0, v6, s14, v0
	v_mul_f32_e32 v0, 0x41800000, v0
	v_cvt_i32_f32_e32 v0, v0
	v_cmp_gt_i32_e64 s[40:41], s10, v5
	s_movk_i32 s10, 0x5f
	v_cmp_lt_i32_e64 s[42:43], s10, v5
	s_add_i32 s10, 0, 0x18000
	s_add_i32 s59, s59, 4
	s_add_i32 s60, s13, 0
	v_lshl_add_u32 v213, v5, 2, s10
	s_lshl_b32 s10, s21, 15
	v_min_i32_e32 v0, 15, v0
	s_add_u32 s10, s62, s10
	v_add_u32_e32 v11, 16, v0
	s_addc_u32 s11, s63, 0
	v_lshlrev_b32_e32 v0, 4, v3
	v_lshl_add_u64 v[134:135], s[10:11], 0, v[0:1]
	v_and_b32_e32 v6, 63, v5
	v_readlane_b32 s10, v251, 32
	v_lshrrev_b32_e32 v7, 6, v5
	v_readlane_b32 s11, v251, 33
	v_add_u32_e32 v12, s12, v0
	v_readlane_b32 s68, v250, 19
	v_lshlrev_b32_e32 v6, 4, v6
	v_lshl_or_b32 v6, v7, 14, v6
	v_mov_b32_e32 v7, 0
	v_lshl_add_u64 v[136:137], v[6:7], 0, s[10:11]
	s_movk_i32 s10, 0xe0
	v_cmp_gt_u32_e32 vcc, s10, v5
	s_movk_i32 s10, 0x6f
	v_readlane_b32 s78, v250, 29
	v_cndmask_b32_e32 v0, 31, v11, vcc
	v_cmp_lt_u32_e32 vcc, s10, v5
	v_readlane_b32 s79, v250, 30
	v_or_b32_e32 v2, s20, v8
	v_cndmask_b32_e32 v0, v10, v0, vcc
	v_lshl_or_b32 v6, v0, 3, s54
	v_ashrrev_i32_e32 v7, 31, v6
	v_ashrrev_i32_e32 v0, 3, v5
	v_lshl_add_u64 v[138:139], v[6:7], 2, s[78:79]
	v_lshlrev_b32_e32 v140, 6, v0
	v_mul_lo_u32 v6, v0, s87
	v_add_u32_e32 v0, 0x200, v5
	v_ashrrev_i32_e32 v0, 3, v0
	v_lshlrev_b32_e32 v142, 6, v0
	v_mul_lo_u32 v7, v0, s87
	v_add_u32_e32 v0, 0x400, v5
	v_ashrrev_i32_e32 v0, 3, v0
	v_ashrrev_i32_e32 v3, 31, v2
	v_lshlrev_b32_e32 v144, 6, v0
	v_mul_lo_u32 v10, v0, s87
	v_add_u32_e32 v0, 0x600, v5
	v_lshlrev_b64 v[2:3], 11, v[2:3]
	v_ashrrev_i32_e32 v0, 3, v0
	s_lshl_b32 s21, s21, 10
	s_lshl_b32 s10, s22, 7
	v_lshl_add_u64 v[2:3], s[36:37], 0, v[2:3]
	v_lshlrev_b32_e32 v146, 6, v0
	v_mul_lo_u32 v11, v0, s87
	v_lshlrev_b32_e32 v0, 3, v9
	s_add_i32 s10, s21, s10
	v_lshl_add_u64 v[150:151], v[2:3], 0, v[0:1]
	v_lshl_or_b32 v0, v8, 2, s10
	v_mov_b32_e32 v5, v1
	v_sub_u32_e32 v0, v0, v4
	s_mov_b32 s13, 0
	s_or_b32 s86, s20, 31
	s_sub_i32 s20, s20, 63
	v_ashrrev_i32_e32 v141, 31, v140
	v_ashrrev_i32_e32 v143, 31, v142
	v_ashrrev_i32_e32 v145, 31, v144
	v_ashrrev_i32_e32 v147, 31, v146
	v_lshl_add_u64 v[148:149], s[0:1], 0, v[4:5]
	v_add_u32_e32 v214, 0, v0
	s_add_i32 s22, s61, 0x8400
	v_add_u32_e32 v215, v12, v6
	v_add_u32_e32 v216, v12, v7
	v_add_u32_e32 v217, v12, v10
	v_add_u32_e32 v218, v12, v11
	s_mov_b64 s[10:11], -1
	v_readlane_b32 s69, v250, 20
	v_readlane_b32 s70, v250, 21
	v_readlane_b32 s71, v250, 22
	v_readlane_b32 s72, v250, 23
	v_readlane_b32 s73, v250, 24
	v_readlane_b32 s74, v250, 25
	v_readlane_b32 s75, v250, 26
	v_readlane_b32 s76, v250, 27
	v_readlane_b32 s77, v250, 28
	v_readlane_b32 s80, v250, 31
	v_readlane_b32 s81, v250, 32
	v_readlane_b32 s82, v250, 33
	v_readlane_b32 s83, v250, 34
	s_branch .LBB0_504

.LBB0_527:
	s_mov_b32 s100, 0x1000
	s_mov_b32 s101, 0
	v_lshl_add_u64 v[160:161], s[100:101], 0, v[136:137]
	v_lshl_add_u64 v[162:163], s[100:101], 1, v[136:137]
	v_lshl_add_u64 v[164:165], s[100:101], 0, v[162:163]
	global_load_dwordx4 v[98:101], v[136:137], off offset:3072
	global_load_dwordx4 v[94:97], v[136:137], off offset:2048
	global_load_dwordx4 v[82:85], v[136:137], off offset:1024
	global_load_dwordx4 v[70:73], v[136:137], off
	global_load_dwordx4 v[118:121], v[160:161], off offset:3072
	global_load_dwordx4 v[110:113], v[160:161], off offset:2048
	global_load_dwordx4 v[106:109], v[160:161], off offset:1024
	global_load_dwordx4 v[102:105], v[160:161], off
	global_load_dwordx4 v[114:117], v[162:163], off offset:3072
	global_load_dwordx4 v[122:125], v[162:163], off offset:2048
	global_load_dwordx4 v[130:133], v[162:163], off offset:1024
	global_load_dwordx4 v[126:129], v[162:163], off
	global_load_dwordx4 v[78:81], v[164:165], off offset:2048
	global_load_dwordx4 v[86:89], v[164:165], off offset:1024
	global_load_dwordx4 v[90:93], v[164:165], off
	global_load_dwordx4 v[74:77], v[164:165], off offset:3072
	v_mul_f32_e32 v152, s19, v0
	global_load_dwordx4 v[66:69], v[148:149], off
	s_waitcnt vmcnt(0)
	v_pk_fma_f32 v[168:169], v[62:63], v[152:153], v[98:99] op_sel_hi:[1,0,1] neg_lo:[1,0,0] neg_hi:[1,0,0]
	v_pk_fma_f32 v[164:165], v[58:59], v[152:153], v[94:95] op_sel_hi:[1,0,1] neg_lo:[1,0,0] neg_hi:[1,0,0]
	v_pk_fma_f32 v[160:161], v[54:55], v[152:153], v[82:83] op_sel_hi:[1,0,1] neg_lo:[1,0,0] neg_hi:[1,0,0]
	v_pk_fma_f32 v[156:157], v[50:51], v[152:153], v[70:71] op_sel_hi:[1,0,1] neg_lo:[1,0,0] neg_hi:[1,0,0]
	v_pk_fma_f32 v[154:155], v[52:53], v[152:153], v[72:73] op_sel_hi:[1,0,1] neg_lo:[1,0,0] neg_hi:[1,0,0]
	v_mul_f32_e32 v70, v157, v157
	v_pk_fma_f32 v[70:71], v[156:157], v[156:157], v[70:71] op_sel_hi:[1,1,0]
	v_mul_f32_e32 v72, v155, v155
	v_pk_fma_f32 v[70:71], v[154:155], v[154:155], v[70:71]
	v_pk_fma_f32 v[158:159], v[56:57], v[152:153], v[84:85] op_sel_hi:[1,0,1] neg_lo:[1,0,0] neg_hi:[1,0,0]
	v_pk_add_f32 v[162:163], v[72:73], v[70:71] op_sel_hi:[0,1]
	v_pk_fma_f32 v[82:83], v[160:161], v[160:161], v[162:163]
	v_mul_f32_e32 v84, v161, v161
	v_pk_add_f32 v[82:83], v[84:85], v[82:83] op_sel_hi:[0,1]
	v_pk_fma_f32 v[82:83], v[158:159], v[158:159], v[82:83]
	v_mul_f32_e32 v84, v159, v159
	v_pk_add_f32 v[166:167], v[84:85], v[82:83] op_sel_hi:[0,1]
	v_pk_fma_f32 v[162:163], v[60:61], v[152:153], v[96:97] op_sel_hi:[1,0,1] neg_lo:[1,0,0] neg_hi:[1,0,0]
	v_pk_fma_f32 v[94:95], v[164:165], v[164:165], v[166:167]
	v_mul_f32_e32 v96, v165, v165
	v_pk_add_f32 v[94:95], v[96:97], v[94:95] op_sel_hi:[0,1]
	v_pk_fma_f32 v[94:95], v[162:163], v[162:163], v[94:95]
	v_mul_f32_e32 v96, v163, v163
	v_pk_add_f32 v[170:171], v[96:97], v[94:95] op_sel_hi:[0,1]
	v_pk_fma_f32 v[166:167], v[64:65], v[152:153], v[100:101] op_sel_hi:[1,0,1] neg_lo:[1,0,0] neg_hi:[1,0,0]
	v_pk_fma_f32 v[98:99], v[168:169], v[168:169], v[170:171]
	v_mul_f32_e32 v100, v169, v169
	v_pk_add_f32 v[98:99], v[100:101], v[98:99] op_sel_hi:[0,1]
	v_pk_fma_f32 v[98:99], v[166:167], v[166:167], v[98:99]
	v_mul_f32_e32 v100, v167, v167
	v_pk_add_f32 v[174:175], v[100:101], v[98:99] op_sel_hi:[0,1]
	v_pk_fma_f32 v[172:173], v[34:35], v[152:153], v[102:103] op_sel_hi:[1,0,1] neg_lo:[1,0,0] neg_hi:[1,0,0]
	v_pk_fma_f32 v[170:171], v[36:37], v[152:153], v[104:105] op_sel_hi:[1,0,1] neg_lo:[1,0,0] neg_hi:[1,0,0]
	v_pk_fma_f32 v[102:103], v[172:173], v[172:173], v[174:175]
	v_mul_f32_e32 v104, v173, v173
	v_pk_add_f32 v[102:103], v[104:105], v[102:103] op_sel_hi:[0,1]
	v_pk_fma_f32 v[102:103], v[170:171], v[170:171], v[102:103]
	v_mul_f32_e32 v104, v171, v171
	v_pk_add_f32 v[178:179], v[104:105], v[102:103] op_sel_hi:[0,1]
	v_pk_fma_f32 v[176:177], v[38:39], v[152:153], v[106:107] op_sel_hi:[1,0,1] neg_lo:[1,0,0] neg_hi:[1,0,0]
	global_load_dwordx4 v[70:73], v[148:149], off offset:32
	v_pk_fma_f32 v[174:175], v[40:41], v[152:153], v[108:109] op_sel_hi:[1,0,1] neg_lo:[1,0,0] neg_hi:[1,0,0]
	v_pk_fma_f32 v[106:107], v[176:177], v[176:177], v[178:179]
	v_mul_f32_e32 v108, v177, v177
	v_pk_add_f32 v[106:107], v[108:109], v[106:107] op_sel_hi:[0,1]
	v_pk_fma_f32 v[106:107], v[174:175], v[174:175], v[106:107]
	v_mul_f32_e32 v108, v175, v175
	global_load_dwordx4 v[82:85], v[148:149], off offset:64
	global_load_dwordx4 v[94:97], v[148:149], off offset:96
	v_pk_add_f32 v[182:183], v[108:109], v[106:107] op_sel_hi:[0,1]
	v_pk_fma_f32 v[180:181], v[42:43], v[152:153], v[110:111] op_sel_hi:[1,0,1] neg_lo:[1,0,0] neg_hi:[1,0,0]
	v_pk_fma_f32 v[178:179], v[44:45], v[152:153], v[112:113] op_sel_hi:[1,0,1] neg_lo:[1,0,0] neg_hi:[1,0,0]
	v_pk_fma_f32 v[110:111], v[180:181], v[180:181], v[182:183]
	v_mul_f32_e32 v112, v181, v181
	v_pk_add_f32 v[110:111], v[112:113], v[110:111] op_sel_hi:[0,1]
	v_pk_fma_f32 v[110:111], v[178:179], v[178:179], v[110:111]
	v_mul_f32_e32 v112, v179, v179
	v_pk_add_f32 v[186:187], v[112:113], v[110:111] op_sel_hi:[0,1]
	v_pk_fma_f32 v[184:185], v[46:47], v[152:153], v[118:119] op_sel_hi:[1,0,1] neg_lo:[1,0,0] neg_hi:[1,0,0]
	v_pk_fma_f32 v[182:183], v[48:49], v[152:153], v[120:121] op_sel_hi:[1,0,1] neg_lo:[1,0,0] neg_hi:[1,0,0]
	v_pk_fma_f32 v[118:119], v[184:185], v[184:185], v[186:187]
	v_mul_f32_e32 v120, v185, v185
	global_load_dwordx4 v[98:101], v[148:149], off offset:128
	global_load_dwordx4 v[102:105], v[148:149], off offset:160
	v_pk_add_f32 v[118:119], v[120:121], v[118:119] op_sel_hi:[0,1]
	v_pk_fma_f32 v[118:119], v[182:183], v[182:183], v[118:119]
	v_mul_f32_e32 v120, v183, v183
	v_pk_add_f32 v[190:191], v[120:121], v[118:119] op_sel_hi:[0,1]
	v_pk_fma_f32 v[188:189], v[18:19], v[152:153], v[126:127] op_sel_hi:[1,0,1] neg_lo:[1,0,0] neg_hi:[1,0,0]
	v_pk_fma_f32 v[186:187], v[20:21], v[152:153], v[128:129] op_sel_hi:[1,0,1] neg_lo:[1,0,0] neg_hi:[1,0,0]
	v_pk_fma_f32 v[126:127], v[188:189], v[188:189], v[190:191]
	v_mul_f32_e32 v128, v189, v189
	v_pk_add_f32 v[126:127], v[128:129], v[126:127] op_sel_hi:[0,1]
	v_pk_fma_f32 v[126:127], v[186:187], v[186:187], v[126:127]
	v_mul_f32_e32 v128, v187, v187
	global_load_dwordx4 v[106:109], v[148:149], off offset:192
	global_load_dwordx4 v[110:113], v[148:149], off offset:224
	v_pk_add_f32 v[194:195], v[128:129], v[126:127] op_sel_hi:[0,1]
	v_pk_fma_f32 v[192:193], v[22:23], v[152:153], v[130:131] op_sel_hi:[1,0,1] neg_lo:[1,0,0] neg_hi:[1,0,0]
	v_pk_fma_f32 v[190:191], v[24:25], v[152:153], v[132:133] op_sel_hi:[1,0,1] neg_lo:[1,0,0] neg_hi:[1,0,0]
	v_pk_fma_f32 v[130:131], v[192:193], v[192:193], v[194:195]
	v_mul_f32_e32 v132, v193, v193
	v_pk_add_f32 v[130:131], v[132:133], v[130:131] op_sel_hi:[0,1]
	v_pk_fma_f32 v[130:131], v[190:191], v[190:191], v[130:131]
	v_mul_f32_e32 v132, v191, v191
	v_pk_add_f32 v[198:199], v[132:133], v[130:131] op_sel_hi:[0,1]
	v_pk_fma_f32 v[196:197], v[26:27], v[152:153], v[122:123] op_sel_hi:[1,0,1] neg_lo:[1,0,0] neg_hi:[1,0,0]
	v_pk_fma_f32 v[194:195], v[28:29], v[152:153], v[124:125] op_sel_hi:[1,0,1] neg_lo:[1,0,0] neg_hi:[1,0,0]
	v_pk_fma_f32 v[122:123], v[196:197], v[196:197], v[198:199]
	v_mul_f32_e32 v124, v197, v197
	global_load_dwordx4 v[118:121], v[148:149], off offset:256
	global_load_dwordx4 v[126:129], v[148:149], off offset:288
	v_pk_add_f32 v[122:123], v[124:125], v[122:123] op_sel_hi:[0,1]
	v_pk_fma_f32 v[122:123], v[194:195], v[194:195], v[122:123]
	v_mul_f32_e32 v124, v195, v195
	v_pk_add_f32 v[202:203], v[124:125], v[122:123] op_sel_hi:[0,1]
	v_pk_fma_f32 v[200:201], v[30:31], v[152:153], v[114:115] op_sel_hi:[1,0,1] neg_lo:[1,0,0] neg_hi:[1,0,0]
	v_pk_fma_f32 v[198:199], v[32:33], v[152:153], v[116:117] op_sel_hi:[1,0,1] neg_lo:[1,0,0] neg_hi:[1,0,0]
	v_pk_fma_f32 v[114:115], v[200:201], v[200:201], v[202:203]
	v_mul_f32_e32 v116, v201, v201
	v_pk_add_f32 v[114:115], v[116:117], v[114:115] op_sel_hi:[0,1]
	v_pk_fma_f32 v[114:115], v[198:199], v[198:199], v[114:115]
	v_mul_f32_e32 v116, v199, v199
	global_load_dwordx4 v[130:133], v[148:149], off offset:320
	global_load_dwordx4 v[122:125], v[148:149], off offset:352
	v_pk_add_f32 v[220:221], v[116:117], v[114:115] op_sel_hi:[0,1]
	v_pk_fma_f32 v[222:223], v[2:3], v[152:153], v[90:91] op_sel_hi:[1,0,1] neg_lo:[1,0,0] neg_hi:[1,0,0]
	v_pk_fma_f32 v[202:203], v[4:5], v[152:153], v[92:93] op_sel_hi:[1,0,1] neg_lo:[1,0,0] neg_hi:[1,0,0]
	v_pk_fma_f32 v[90:91], v[222:223], v[222:223], v[220:221]
	v_mul_f32_e32 v92, v223, v223
	v_pk_add_f32 v[90:91], v[92:93], v[90:91] op_sel_hi:[0,1]
	v_pk_fma_f32 v[90:91], v[202:203], v[202:203], v[90:91]
	v_mul_f32_e32 v92, v203, v203
	v_pk_add_f32 v[220:221], v[92:93], v[90:91] op_sel_hi:[0,1]
	v_pk_fma_f32 v[226:227], v[6:7], v[152:153], v[86:87] op_sel_hi:[1,0,1] neg_lo:[1,0,0] neg_hi:[1,0,0]
	v_pk_fma_f32 v[224:225], v[8:9], v[152:153], v[88:89] op_sel_hi:[1,0,1] neg_lo:[1,0,0] neg_hi:[1,0,0]
	v_pk_fma_f32 v[86:87], v[226:227], v[226:227], v[220:221]
	v_mul_f32_e32 v88, v227, v227
	global_load_dwordx4 v[114:117], v[148:149], off offset:384
	global_load_dwordx4 v[90:93], v[148:149], off offset:416
	v_pk_add_f32 v[86:87], v[88:89], v[86:87] op_sel_hi:[0,1]
	v_pk_fma_f32 v[86:87], v[224:225], v[224:225], v[86:87]
	v_mul_f32_e32 v88, v225, v225
	v_pk_add_f32 v[220:221], v[88:89], v[86:87] op_sel_hi:[0,1]
	v_pk_fma_f32 v[230:231], v[10:11], v[152:153], v[78:79] op_sel_hi:[1,0,1] neg_lo:[1,0,0] neg_hi:[1,0,0]
	v_pk_fma_f32 v[228:229], v[12:13], v[152:153], v[80:81] op_sel_hi:[1,0,1] neg_lo:[1,0,0] neg_hi:[1,0,0]
	v_pk_fma_f32 v[78:79], v[230:231], v[230:231], v[220:221]
	v_mul_f32_e32 v80, v231, v231
	v_pk_add_f32 v[78:79], v[80:81], v[78:79] op_sel_hi:[0,1]
	v_pk_fma_f32 v[78:79], v[228:229], v[228:229], v[78:79]
	v_mul_f32_e32 v80, v229, v229
	global_load_dwordx4 v[86:89], v[148:149], off offset:448
	v_pk_add_f32 v[220:221], v[80:81], v[78:79] op_sel_hi:[0,1]
	v_pk_fma_f32 v[74:75], v[14:15], v[152:153], v[74:75] op_sel_hi:[1,0,1] neg_lo:[1,0,0] neg_hi:[1,0,0]
	v_pk_fma_f32 v[76:77], v[16:17], v[152:153], v[76:77] op_sel_hi:[1,0,1] neg_lo:[1,0,0] neg_hi:[1,0,0]
	v_pk_fma_f32 v[152:153], v[74:75], v[74:75], v[220:221]
	v_mul_f32_e32 v220, v75, v75
	v_pk_add_f32 v[152:153], v[220:221], v[152:153] op_sel_hi:[0,1]
	global_load_dwordx4 v[78:81], v[148:149], off offset:480
	v_pk_fma_f32 v[152:153], v[76:77], v[76:77], v[152:153]
	v_mul_f32_e32 v220, v77, v77
	v_pk_add_f32 v[152:153], v[220:221], v[152:153] op_sel_hi:[0,1]
	v_mov_b32_e32 v153, v152
	s_nop 1
	v_permlane32_swap_b32_e32 v152, v153
	v_add_f32_e32 v152, v152, v153
	v_fmamk_f32 v152, v152, 0x3c000000, v240
	v_cmp_gt_f32_e32 vcc, s31, v152
	v_mul_f32_e32 v153, 0x4f800000, v152
	s_nop 0
	v_cndmask_b32_e32 v152, v152, v153, vcc
	v_sqrt_f32_e32 v153, v152
	s_nop 0
	v_add_u32_e32 v219, -1, v153
	v_fma_f32 v220, -v219, v153, v152
	v_cmp_ge_f32_e64 s[44:45], 0, v220
	v_add_u32_e32 v220, 1, v153
	s_nop 0
	v_cndmask_b32_e64 v219, v153, v219, s[44:45]
	v_fma_f32 v153, -v220, v153, v152
	v_cmp_lt_f32_e64 s[44:45], 0, v153
	s_nop 1
	v_cndmask_b32_e64 v153, v219, v220, s[44:45]
	v_mul_f32_e32 v219, 0x37800000, v153
	v_cndmask_b32_e32 v153, v153, v219, vcc
	v_cmp_class_f32_e32 vcc, v152, v241
	s_nop 1
	v_cndmask_b32_e32 v152, v153, v152, vcc
	v_div_scale_f32 v153, s[24:25], v152, v152, v204
	v_rcp_f32_e32 v219, v153
	s_nop 0
	v_fma_f32 v220, -v153, v219, 1.0
	v_fmac_f32_e32 v219, v220, v219
	v_div_scale_f32 v220, vcc, v204, v152, v204
	v_mul_f32_e32 v221, v220, v219
	v_fma_f32 v232, -v153, v221, v220
	v_fmac_f32_e32 v221, v232, v219
	v_fma_f32 v153, -v153, v221, v220
	v_div_fmas_f32 v153, v153, v219, v221
	v_div_fixup_f32 v152, v153, v152, v204
	v_pk_mul_f32 v[156:157], v[156:157], v[152:153] op_sel_hi:[1,0]
	v_pk_mul_f32 v[154:155], v[154:155], v[152:153] op_sel_hi:[1,0]
	v_pk_mul_f32 v[66:67], v[66:67], v[156:157]
	v_pk_mul_f32 v[68:69], v[68:69], v[154:155]
	v_cvt_pk_bf16_f32 v66, v66, v67
	v_cvt_pk_bf16_f32 v67, v68, v69
	global_store_dwordx2 v[150:151], v[66:67], off
	v_pk_mul_f32 v[66:67], v[160:161], v[152:153] op_sel_hi:[1,0]
	v_pk_mul_f32 v[68:69], v[158:159], v[152:153] op_sel_hi:[1,0]
	s_waitcnt vmcnt(0)
	v_pk_mul_f32 v[66:67], v[70:71], v[66:67]
	v_pk_mul_f32 v[68:69], v[72:73], v[68:69]
	v_cvt_pk_bf16_f32 v66, v66, v67
	v_cvt_pk_bf16_f32 v67, v68, v69
	global_store_dwordx2 v[150:151], v[66:67], off offset:16
	v_pk_mul_f32 v[66:67], v[164:165], v[152:153] op_sel_hi:[1,0]
	v_pk_mul_f32 v[68:69], v[162:163], v[152:153] op_sel_hi:[1,0]
	v_pk_mul_f32 v[66:67], v[82:83], v[66:67]
	v_pk_mul_f32 v[68:69], v[84:85], v[68:69]
	v_cvt_pk_bf16_f32 v66, v66, v67
	v_cvt_pk_bf16_f32 v67, v68, v69
	global_store_dwordx2 v[150:151], v[66:67], off offset:32
	v_pk_mul_f32 v[66:67], v[168:169], v[152:153] op_sel_hi:[1,0]
	v_pk_mul_f32 v[68:69], v[166:167], v[152:153] op_sel_hi:[1,0]
	v_pk_mul_f32 v[66:67], v[94:95], v[66:67]
	v_pk_mul_f32 v[68:69], v[96:97], v[68:69]
	v_cvt_pk_bf16_f32 v66, v66, v67
	v_cvt_pk_bf16_f32 v67, v68, v69
	global_store_dwordx2 v[150:151], v[66:67], off offset:48
	v_pk_mul_f32 v[66:67], v[172:173], v[152:153] op_sel_hi:[1,0]
	v_pk_mul_f32 v[68:69], v[170:171], v[152:153] op_sel_hi:[1,0]
	v_pk_mul_f32 v[66:67], v[66:67], v[98:99]
	v_pk_mul_f32 v[68:69], v[68:69], v[100:101]
	v_cvt_pk_bf16_f32 v66, v66, v67
	v_cvt_pk_bf16_f32 v67, v68, v69
	global_store_dwordx2 v[150:151], v[66:67], off offset:64
	v_pk_mul_f32 v[66:67], v[176:177], v[152:153] op_sel_hi:[1,0]
	v_pk_mul_f32 v[68:69], v[174:175], v[152:153] op_sel_hi:[1,0]
	v_pk_mul_f32 v[66:67], v[66:67], v[102:103]
	v_pk_mul_f32 v[68:69], v[68:69], v[104:105]
	v_cvt_pk_bf16_f32 v66, v66, v67
	v_cvt_pk_bf16_f32 v67, v68, v69
	global_store_dwordx2 v[150:151], v[66:67], off offset:80
	v_pk_mul_f32 v[66:67], v[180:181], v[152:153] op_sel_hi:[1,0]
	v_pk_mul_f32 v[68:69], v[178:179], v[152:153] op_sel_hi:[1,0]
	v_pk_mul_f32 v[66:67], v[66:67], v[106:107]
	v_pk_mul_f32 v[68:69], v[68:69], v[108:109]
	v_cvt_pk_bf16_f32 v66, v66, v67
	v_cvt_pk_bf16_f32 v67, v68, v69
	global_store_dwordx2 v[150:151], v[66:67], off offset:96
	v_pk_mul_f32 v[66:67], v[184:185], v[152:153] op_sel_hi:[1,0]
	v_pk_mul_f32 v[68:69], v[182:183], v[152:153] op_sel_hi:[1,0]
	v_pk_mul_f32 v[66:67], v[66:67], v[110:111]
	v_pk_mul_f32 v[68:69], v[68:69], v[112:113]
	v_cvt_pk_bf16_f32 v66, v66, v67
	v_cvt_pk_bf16_f32 v67, v68, v69
	global_store_dwordx2 v[150:151], v[66:67], off offset:112
	v_pk_mul_f32 v[66:67], v[188:189], v[152:153] op_sel_hi:[1,0]
	v_pk_mul_f32 v[68:69], v[186:187], v[152:153] op_sel_hi:[1,0]
	v_pk_mul_f32 v[66:67], v[66:67], v[118:119]
	v_pk_mul_f32 v[68:69], v[68:69], v[120:121]
	v_cvt_pk_bf16_f32 v66, v66, v67
	v_cvt_pk_bf16_f32 v67, v68, v69
	global_store_dwordx2 v[150:151], v[66:67], off offset:128
	v_pk_mul_f32 v[66:67], v[192:193], v[152:153] op_sel_hi:[1,0]
	v_pk_mul_f32 v[68:69], v[190:191], v[152:153] op_sel_hi:[1,0]
	v_pk_mul_f32 v[66:67], v[66:67], v[126:127]
	v_pk_mul_f32 v[68:69], v[68:69], v[128:129]
	v_cvt_pk_bf16_f32 v66, v66, v67
	v_cvt_pk_bf16_f32 v67, v68, v69
	global_store_dwordx2 v[150:151], v[66:67], off offset:144
	v_pk_mul_f32 v[66:67], v[196:197], v[152:153] op_sel_hi:[1,0]
	v_pk_mul_f32 v[68:69], v[194:195], v[152:153] op_sel_hi:[1,0]
	v_pk_mul_f32 v[66:67], v[66:67], v[130:131]
	v_pk_mul_f32 v[68:69], v[68:69], v[132:133]
	v_cvt_pk_bf16_f32 v66, v66, v67
	v_cvt_pk_bf16_f32 v67, v68, v69
	global_store_dwordx2 v[150:151], v[66:67], off offset:160
	v_pk_mul_f32 v[66:67], v[200:201], v[152:153] op_sel_hi:[1,0]
	v_pk_mul_f32 v[68:69], v[198:199], v[152:153] op_sel_hi:[1,0]
	v_pk_mul_f32 v[66:67], v[66:67], v[122:123]
	v_pk_mul_f32 v[68:69], v[68:69], v[124:125]
	v_cvt_pk_bf16_f32 v66, v66, v67
	v_cvt_pk_bf16_f32 v67, v68, v69
	global_store_dwordx2 v[150:151], v[66:67], off offset:176
	v_pk_mul_f32 v[66:67], v[222:223], v[152:153] op_sel_hi:[1,0]
	v_pk_mul_f32 v[68:69], v[202:203], v[152:153] op_sel_hi:[1,0]
	v_pk_mul_f32 v[66:67], v[66:67], v[114:115]
	v_pk_mul_f32 v[68:69], v[68:69], v[116:117]
	v_cvt_pk_bf16_f32 v66, v66, v67
	v_cvt_pk_bf16_f32 v67, v68, v69
	global_store_dwordx2 v[150:151], v[66:67], off offset:192
	v_pk_mul_f32 v[66:67], v[226:227], v[152:153] op_sel_hi:[1,0]
	v_pk_mul_f32 v[68:69], v[224:225], v[152:153] op_sel_hi:[1,0]
	v_pk_mul_f32 v[66:67], v[66:67], v[90:91]
	v_pk_mul_f32 v[68:69], v[68:69], v[92:93]
	v_cvt_pk_bf16_f32 v66, v66, v67
	v_cvt_pk_bf16_f32 v67, v68, v69
	global_store_dwordx2 v[150:151], v[66:67], off offset:208
	v_pk_mul_f32 v[66:67], v[230:231], v[152:153] op_sel_hi:[1,0]
	v_pk_mul_f32 v[68:69], v[228:229], v[152:153] op_sel_hi:[1,0]
	v_pk_mul_f32 v[66:67], v[66:67], v[86:87]
	v_pk_mul_f32 v[68:69], v[68:69], v[88:89]
	v_cvt_pk_bf16_f32 v66, v66, v67
	v_cvt_pk_bf16_f32 v67, v68, v69
	global_store_dwordx2 v[150:151], v[66:67], off offset:224
	v_pk_mul_f32 v[66:67], v[74:75], v[152:153] op_sel_hi:[1,0]
	v_pk_mul_f32 v[68:69], v[76:77], v[152:153] op_sel_hi:[1,0]
	v_pk_mul_f32 v[66:67], v[66:67], v[78:79]
	v_pk_mul_f32 v[68:69], v[68:69], v[80:81]
	v_cvt_pk_bf16_f32 v66, v66, v67
	v_cvt_pk_bf16_f32 v67, v68, v69
	global_store_dwordx2 v[150:151], v[66:67], off offset:240
	s_cbranch_execnz .LBB0_503
.LBB0_528:
	s_mov_b32 s100, 0x1000
	s_mov_b32 s101, 0
	v_lshl_add_u64 v[70:71], s[100:101], 0, v[136:137]
	v_lshl_add_u64 v[72:73], s[100:101], 1, v[136:137]
	v_lshl_add_u64 v[74:75], s[100:101], 0, v[72:73]
	v_pk_mul_f32 v[50:51], v[50:51], v[0:1] op_sel_hi:[1,0]
	v_pk_mul_f32 v[52:53], v[52:53], v[0:1] op_sel_hi:[1,0]
	v_pk_mul_f32 v[34:35], v[34:35], v[0:1] op_sel_hi:[1,0]
	v_pk_mul_f32 v[36:37], v[36:37], v[0:1] op_sel_hi:[1,0]
	v_pk_mul_f32 v[18:19], v[18:19], v[0:1] op_sel_hi:[1,0]
	v_pk_mul_f32 v[20:21], v[20:21], v[0:1] op_sel_hi:[1,0]
	v_pk_mul_f32 v[2:3], v[2:3], v[0:1] op_sel_hi:[1,0]
	v_pk_mul_f32 v[4:5], v[4:5], v[0:1] op_sel_hi:[1,0]
	global_store_dwordx4 v[136:137], v[50:53], off
	global_store_dwordx4 v[70:71], v[34:37], off
	global_store_dwordx4 v[72:73], v[18:21], off
	v_pk_mul_f32 v[50:51], v[54:55], v[0:1] op_sel_hi:[1,0]
	v_pk_mul_f32 v[52:53], v[56:57], v[0:1] op_sel_hi:[1,0]
	v_pk_mul_f32 v[34:35], v[38:39], v[0:1] op_sel_hi:[1,0]
	v_pk_mul_f32 v[36:37], v[40:41], v[0:1] op_sel_hi:[1,0]
	v_pk_mul_f32 v[18:19], v[22:23], v[0:1] op_sel_hi:[1,0]
	v_pk_mul_f32 v[20:21], v[24:25], v[0:1] op_sel_hi:[1,0]
	global_store_dwordx4 v[74:75], v[2:5], off
	global_store_dwordx4 v[136:137], v[50:53], off offset:1024
	global_store_dwordx4 v[70:71], v[34:37], off offset:1024
	v_pk_mul_f32 v[2:3], v[6:7], v[0:1] op_sel_hi:[1,0]
	v_pk_mul_f32 v[4:5], v[8:9], v[0:1] op_sel_hi:[1,0]
	v_pk_mul_f32 v[50:51], v[58:59], v[0:1] op_sel_hi:[1,0]
	v_pk_mul_f32 v[52:53], v[60:61], v[0:1] op_sel_hi:[1,0]
	v_pk_mul_f32 v[34:35], v[42:43], v[0:1] op_sel_hi:[1,0]
	v_pk_mul_f32 v[36:37], v[44:45], v[0:1] op_sel_hi:[1,0]
	global_store_dwordx4 v[72:73], v[18:21], off offset:1024
	global_store_dwordx4 v[74:75], v[2:5], off offset:1024
	global_store_dwordx4 v[136:137], v[50:53], off offset:2048
	v_pk_mul_f32 v[18:19], v[26:27], v[0:1] op_sel_hi:[1,0]
	v_pk_mul_f32 v[20:21], v[28:29], v[0:1] op_sel_hi:[1,0]
	v_pk_mul_f32 v[2:3], v[10:11], v[0:1] op_sel_hi:[1,0]
	v_pk_mul_f32 v[4:5], v[12:13], v[0:1] op_sel_hi:[1,0]
	v_pk_mul_f32 v[50:51], v[62:63], v[0:1] op_sel_hi:[1,0]
	v_pk_mul_f32 v[52:53], v[64:65], v[0:1] op_sel_hi:[1,0]
	global_store_dwordx4 v[70:71], v[34:37], off offset:2048
	global_store_dwordx4 v[72:73], v[18:21], off offset:2048
	global_store_dwordx4 v[74:75], v[2:5], off offset:2048
	v_pk_mul_f32 v[34:35], v[46:47], v[0:1] op_sel_hi:[1,0]
	v_pk_mul_f32 v[36:37], v[48:49], v[0:1] op_sel_hi:[1,0]
	v_pk_mul_f32 v[18:19], v[30:31], v[0:1] op_sel_hi:[1,0]
	v_pk_mul_f32 v[20:21], v[32:33], v[0:1] op_sel_hi:[1,0]
	v_pk_mul_f32 v[2:3], v[14:15], v[0:1] op_sel_hi:[1,0]
	v_pk_mul_f32 v[4:5], v[16:17], v[0:1] op_sel_hi:[1,0]
	global_store_dwordx4 v[136:137], v[50:53], off offset:3072
	global_store_dwordx4 v[70:71], v[34:37], off offset:3072
	global_store_dwordx4 v[72:73], v[18:21], off offset:3072
	global_store_dwordx4 v[74:75], v[2:5], off offset:3072
	s_branch .LBB0_503
